# NSA softmax sums: half-dead packed adds -> single v_add_f32, dead x+x adds deleted (bit-identical)
# speedup vs baseline: 1.0040x; 1.0040x over previous
; #define LAS __attribute__((address_space(3)))
; #define MFMA32(a, b, c) __builtin_amdgcn_mfma_f32_32x32x16_bf16((a), (b), (c), 0, 0, 0)
; DI float fexp2(float x) { return __builtin_amdgcn_exp2f(x); }
; DI s16x4 vtr(const LAS unsigned char* p) { return __builtin_bit_cast(s16x4, __builtin_amdgcn_ds_read_tr16_b64_v4i16((LAS v4i16_t*)p)); }
; DI void flash_pv(FState& st, f32x16& p0, f32x16& p1, bool rowon, const LAS unsigned char* vb, int lane) {
;     ...
;     const float cl = rowon ? SM_C : 0.0f;
;     const float bl = rowon ? ((st.m == NINF) ? 0.0f : -st.m * SM_C) : NINF;
;     float sum = 0.f;
; #pragma unroll
;     for (int r = 0; r < 16; ++r) { p0[r] = fexp2(__builtin_fmaf(p0[r], cl, bl)); p1[r] = fexp2(__builtin_fmaf(p1[r], cl, bl)); sum += p0[r] + p1[r]; }
;     st.l += sum;
;     const int h = lane >> 5;
;     const int vx = (((lane & 15) >> 3) & 1) * 64;
;     const LAS unsigned char* vp = vb + (4 * h + ((lane & 15) >> 2)) * 128 + ((lane >> 4) & 1) * 32 + (lane & 3) * 8;
; #pragma unroll
;     for (int sub = 0; sub < 2; ++sub)
; #pragma unroll
;         for (int s2 = 0; s2 < 2; ++s2) {
;             const bf16x8 pf = pack8h(sub ? p1 : p0, s2);
;             const LAS unsigned char* vq = vp + (32 * sub + 16 * s2) * 128;
;             { const s16x4 lo = vtr(vq + vx), hi = vtr(vq + 1024 + vx); const bf16x8 vf = {lo[0], lo[1], lo[2], lo[3], hi[0], hi[1], hi[2], hi[3]}; st.o0 = MFMA32(vf, pf, st.o0); }
;             { const s16x4 lo = vtr(vq + (64 - vx)), hi = vtr(vq + 1024 + (64 - vx)); const bf16x8 vf = {lo[0], lo[1], lo[2], lo[3], hi[0], hi[1], hi[2], hi[3]}; st.o1 = MFMA32(vf, pf, st.o1); }
;         }
.LBB0_759:
	s_or_b64 exec, exec, s[4:5]
	v_fma_f32 v2, v98, v5, v4
	v_exp_f32_e32 v12, v2
	v_fma_f32 v2, v82, v5, v4
	v_exp_f32_e32 v246, v2
	s_waitcnt lgkmcnt(3)
	v_mfma_f32_32x32x16_bf16 v[130:145], v[226:229], v[154:157], v[130:145]
	v_fma_f32 v2, v99, v5, v4
	v_exp_f32_e32 v6, v2
	v_fma_f32 v2, v83, v5, v4
	v_exp_f32_e32 v2, v2
	v_add_f32_e32 v7, v12, v246
	s_add_i32 s77, s74, 1
	s_cmp_ge_u32 s77, s51
	v_pk_add_f32 v[8:9], v[6:7], v[2:3]
	v_fma_f32 v7, v100, v5, v4
	v_add_f32_e32 v99, v8, v9
	s_waitcnt lgkmcnt(2)
	v_mfma_f32_32x32x16_bf16 v[114:129], v[230:233], v[154:157], v[114:129]
	v_fma_f32 v8, v84, v5, v4
	v_exp_f32_e32 v7, v7
	v_exp_f32_e32 v247, v8
	v_fma_f32 v8, v101, v5, v4
	v_fma_f32 v9, v85, v5, v4
	v_exp_f32_e32 v8, v8
	v_exp_f32_e32 v98, v9
	v_add_f32_e32 v9, v7, v247
	v_cvt_pk_bf16_f32 v6, v12, v6
	v_cvt_pk_bf16_f32 v7, v7, v8
	s_waitcnt lgkmcnt(1)
	v_mfma_f32_32x32x16_bf16 v[130:145], v[234:237], v[158:161], v[130:145]
	v_pk_add_f32 v[10:11], v[8:9], v[98:99]
	v_fma_f32 v9, v102, v5, v4
	v_add_f32_e32 v101, v10, v11
	v_fma_f32 v10, v86, v5, v4
	v_exp_f32_e32 v99, v10
	v_fma_f32 v10, v103, v5, v4
	v_exp_f32_e32 v9, v9
	v_exp_f32_e32 v14, v10
	v_fma_f32 v10, v87, v5, v4
	v_exp_f32_e32 v100, v10
	s_waitcnt lgkmcnt(0)
	v_mfma_f32_32x32x16_bf16 v[114:129], v[238:241], v[158:161], v[114:129]
	v_add_f32_e32 v15, v9, v99
	v_cvt_pk_bf16_f32 v8, v9, v14
	v_pk_add_f32 v[10:11], v[14:15], v[100:101]
	s_nop 0
	v_add_f32_e32 v87, v10, v11
	v_fma_f32 v10, v104, v5, v4
	v_exp_f32_e32 v15, v10
	v_fma_f32 v10, v88, v5, v4
	v_exp_f32_e32 v101, v10
	v_fma_f32 v10, v105, v5, v4
	v_exp_f32_e32 v16, v10
	v_fma_f32 v10, v89, v5, v4
	v_exp_f32_e32 v86, v10
	v_add_f32_e32 v17, v15, v101
	v_cvt_pk_bf16_f32 v9, v15, v16
	v_pk_add_f32 v[10:11], v[16:17], v[86:87]
	s_nop 0
	v_add_f32_e32 v89, v10, v11
	v_fma_f32 v10, v106, v5, v4
	v_exp_f32_e32 v87, v10
	v_fma_f32 v10, v90, v5, v4
	v_exp_f32_e32 v248, v10
	v_fma_f32 v10, v107, v5, v4
	v_exp_f32_e32 v90, v10
	v_fma_f32 v10, v91, v5, v4
	v_exp_f32_e32 v88, v10
	v_fma_f32 v10, v108, v5, v4
	v_exp_f32_e32 v107, v10
	v_fma_f32 v10, v92, v5, v4
	v_add_f32_e32 v91, v87, v248
	v_exp_f32_e32 v108, v10
	v_pk_add_f32 v[10:11], v[90:91], v[88:89]
	v_fma_f32 v91, v112, v5, v4
	v_add_f32_e32 v103, v10, v11
	v_fma_f32 v10, v109, v5, v4
	v_exp_f32_e32 v104, v10
	v_fma_f32 v10, v93, v5, v4
	v_exp_f32_e32 v102, v10
	ds_read_b64_tr_b16 v[10:11], v218 offset:8192
	ds_read_b64_tr_b16 v[12:13], v218 offset:9216
	ds_read_b64_tr_b16 v[14:15], v217 offset:8256
	ds_read_b64_tr_b16 v[16:17], v217 offset:9280
	ds_read_b64_tr_b16 v[82:83], v218 offset:10240
	ds_read_b64_tr_b16 v[84:85], v218 offset:11264
	s_waitcnt lgkmcnt(4)
	v_mfma_f32_32x32x16_bf16 v[66:81], v[10:13], v[6:9], v[66:81]
	v_fma_f32 v10, v110, v5, v4
	v_exp_f32_e32 v89, v10
	v_fma_f32 v10, v111, v5, v4
	v_exp_f32_e32 v92, v10
	v_exp_f32_e32 v109, v91
	v_add_f32_e32 v105, v107, v108
	ds_read_b64_tr_b16 v[10:11], v217 offset:10304
	ds_read_b64_tr_b16 v[12:13], v217 offset:11328
	s_waitcnt lgkmcnt(4)
	v_mfma_f32_32x32x16_bf16 v[50:65], v[14:17], v[6:9], v[50:65]
	v_fma_f32 v6, v113, v5, v4
	v_exp_f32_e32 v106, v6
	v_cvt_pk_bf16_f32 v6, v87, v90
	v_cvt_pk_bf16_f32 v7, v107, v104
	v_cvt_pk_bf16_f32 v8, v89, v92
	v_cvt_pk_bf16_f32 v9, v109, v106
	v_pk_add_f32 v[14:15], v[104:105], v[102:103]
	s_waitcnt lgkmcnt(2)
	v_mfma_f32_32x32x16_bf16 v[66:81], v[82:85], v[6:9], v[66:81]
	v_add_f32_e64 v91, v14, v15
	v_fma_f32 v14, v94, v5, v4
	v_exp_f32_e32 v94, v14
	ds_read_b64_tr_b16 v[14:15], v218 offset:12288
	ds_read_b64_tr_b16 v[16:17], v218 offset:13312
	v_fma_f32 v82, v95, v5, v4
	v_exp_f32_e32 v90, v82
	v_add_f32_e32 v93, v89, v94
	s_waitcnt lgkmcnt(2)
	v_mfma_f32_32x32x16_bf16 v[50:65], v[10:13], v[6:9], v[50:65]
	v_cvt_pk_bf16_f32 v6, v246, v2
	v_cvt_pk_bf16_f32 v7, v247, v98
	v_cvt_pk_bf16_f32 v8, v99, v100
	v_cvt_pk_bf16_f32 v9, v101, v86
	ds_read_b64_tr_b16 v[10:11], v218 offset:14336
	ds_read_b64_tr_b16 v[12:13], v218 offset:15360
	v_pk_add_f32 v[82:83], v[92:93], v[90:91]
	v_fma_f32 v2, v96, v5, v4
	s_waitcnt lgkmcnt(2)
	v_mfma_f32_32x32x16_bf16 v[66:81], v[14:17], v[6:9], v[66:81]
	ds_read_b64_tr_b16 v[14:15], v217 offset:12352
	ds_read_b64_tr_b16 v[16:17], v217 offset:13376
	v_add_f32_e64 v87, v82, v83
	v_fmac_f32_e32 v4, v97, v5
	ds_read_b64_tr_b16 v[82:83], v217 offset:14400
	ds_read_b64_tr_b16 v[84:85], v217 offset:15424
	v_exp_f32_e32 v2, v2
	v_exp_f32_e32 v86, v4
	v_cvt_pk_bf16_f32 v4, v248, v88
	s_waitcnt lgkmcnt(2)
	v_mfma_f32_32x32x16_bf16 v[50:65], v[14:17], v[6:9], v[50:65]
	v_cvt_pk_bf16_f32 v5, v108, v102
	v_cvt_pk_bf16_f32 v6, v94, v90
	v_cvt_pk_bf16_f32 v7, v2, v86
	v_add_f32_e32 v107, v109, v2
	v_add_f32_e64 v8, v106, v86
	v_add_f32_e64 v9, v107, v87
	v_add_f32_e32 v2, v8, v9
	v_mfma_f32_32x32x16_bf16 v[66:81], v[10:13], v[4:7], v[66:81]
	v_add_f32_e32 v214, v214, v2
	s_waitcnt lgkmcnt(0)
	v_mfma_f32_32x32x16_bf16 v[50:65], v[82:85], v[4:7], v[50:65]
	s_cbranch_scc1 .LBB0_780
	s_movk_i32 s76, 0x4000
	s_add_i32 s4, s74, 5
	s_cmp_ge_u32 s4, s51
	s_waitcnt vmcnt(1)
	ds_write_b128 v205, v[182:185] offset:32768
	s_waitcnt vmcnt(0)
	ds_write_b128 v212, v[178:181] offset:40960
	s_waitcnt lgkmcnt(0)
	s_barrier
	s_cbranch_scc1 .LBB0_762
	s_cmp_gt_u32 s4, s69
	s_cselect_b64 s[8:9], -1, 0
	s_mov_b32 s5, s52
	s_and_b64 s[8:9], s[8:9], exec
	s_cselect_b32 s4, s5, s4
	s_cselect_b32 s16, 0x1000, s65
	s_cselect_b32 s8, s64, 0x500
	s_lshl_b32 s4, s4, 6
	s_mov_b32 s9, s17
	v_mad_i64_i32 v[4:5], s[4:5], s4, v199, v[192:193]
	v_lshl_add_u64 v[6:7], v[4:5], 0, s[8:9]
	v_lshl_add_u64 v[4:5], v[4:5], 0, s[16:17]
	global_load_dwordx4 v[182:185], v[6:7], off
	global_load_dwordx4 v[178:181], v[4:5], off

; #define LAS __attribute__((address_space(3)))
; #define MFMA32(a, b, c) __builtin_amdgcn_mfma_f32_32x32x16_bf16((a), (b), (c), 0, 0, 0)
; DI float fexp2(float x) { return __builtin_amdgcn_exp2f(x); }
; DI s16x4 vtr(const LAS unsigned char* p) { return __builtin_bit_cast(s16x4, __builtin_amdgcn_ds_read_tr16_b64_v4i16((LAS v4i16_t*)p)); }
; DI void flash_qk(const LAS unsigned char* kb, const bf16x8 (&qf)[4], f32x16& p0, f32x16& p1, int r32, int h) {
;     ...
;     for (int s = 0; s < 4; ++s) {
;         const int off = r32 * 128 + (((2 * s + h) ^ sw) << 4);
;         const bf16x8 a0 = *(const LAS bf16x8*)(kb + off), a1 = *(const LAS bf16x8*)(kb + off + 4096);
;         p0 = MFMA32(a0, qf[s], p0); p1 = MFMA32(a1, qf[s], p1);
;     }
; DI void flash_pv(FState& st, f32x16& p0, f32x16& p1, bool rowon, const LAS unsigned char* vb, int lane) {
;     ...
;     const float cl = rowon ? SM_C : 0.0f;
;     const float bl = rowon ? ((st.m == NINF) ? 0.0f : -st.m * SM_C) : NINF;
;     float sum = 0.f;
; #pragma unroll
;     for (int r = 0; r < 16; ++r) { p0[r] = fexp2(__builtin_fmaf(p0[r], cl, bl)); p1[r] = fexp2(__builtin_fmaf(p1[r], cl, bl)); sum += p0[r] + p1[r]; }
;     st.l += sum;
;     const int h = lane >> 5;
;     const int vx = (((lane & 15) >> 3) & 1) * 64;
;     const LAS unsigned char* vp = vb + (4 * h + ((lane & 15) >> 2)) * 128 + ((lane >> 4) & 1) * 32 + (lane & 3) * 8;
; #pragma unroll
;     for (int sub = 0; sub < 2; ++sub)
; #pragma unroll
;         for (int s2 = 0; s2 < 2; ++s2) {
;             const bf16x8 pf = pack8h(sub ? p1 : p0, s2);
;             const LAS unsigned char* vq = vp + (32 * sub + 16 * s2) * 128;
;             { const s16x4 lo = vtr(vq + vx), hi = vtr(vq + 1024 + vx); const bf16x8 vf = {lo[0], lo[1], lo[2], lo[3], hi[0], hi[1], hi[2], hi[3]}; st.o0 = MFMA32(vf, pf, st.o0); }
;             { const s16x4 lo = vtr(vq + (64 - vx)), hi = vtr(vq + 1024 + (64 - vx)); const bf16x8 vf = {lo[0], lo[1], lo[2], lo[3], hi[0], hi[1], hi[2], hi[3]}; st.o1 = MFMA32(vf, pf, st.o1); }
;         }
.LBB0_778:
	s_or_b64 exec, exec, s[4:5]
	v_fma_f32 v2, v130, v5, v4
	v_exp_f32_e32 v12, v2
	v_fma_f32 v2, v114, v5, v4
	v_exp_f32_e32 v246, v2
	s_waitcnt lgkmcnt(3)
	v_mfma_f32_32x32x16_bf16 v[98:113], v[226:229], v[154:157], v[98:113]
	v_fma_f32 v2, v131, v5, v4
	v_exp_f32_e32 v6, v2
	v_fma_f32 v2, v115, v5, v4
	v_exp_f32_e32 v2, v2
	v_add_f32_e32 v7, v12, v246
	v_pk_add_f32 v[8:9], v[6:7], v[2:3]
	s_nop 0
	v_add_f32_e32 v131, v8, v9
	v_fma_f32 v7, v132, v5, v4
	v_fma_f32 v8, v116, v5, v4
	s_waitcnt lgkmcnt(2)
	v_mfma_f32_32x32x16_bf16 v[82:97], v[230:233], v[154:157], v[82:97]
	v_exp_f32_e32 v7, v7
	v_exp_f32_e32 v247, v8
	v_fma_f32 v8, v133, v5, v4
	v_fma_f32 v9, v117, v5, v4
	v_exp_f32_e32 v8, v8
	v_exp_f32_e32 v130, v9
	v_add_f32_e32 v9, v7, v247
	v_cvt_pk_bf16_f32 v6, v12, v6
	v_cvt_pk_bf16_f32 v7, v7, v8
	v_pk_add_f32 v[10:11], v[8:9], v[130:131]
	s_waitcnt lgkmcnt(1)
	v_mfma_f32_32x32x16_bf16 v[98:113], v[234:237], v[158:161], v[98:113]
	v_fma_f32 v9, v134, v5, v4
	v_add_f32_e32 v133, v10, v11
	v_fma_f32 v10, v118, v5, v4
	v_exp_f32_e32 v131, v10
	v_fma_f32 v10, v135, v5, v4
	v_exp_f32_e32 v9, v9
	v_exp_f32_e32 v14, v10
	v_fma_f32 v10, v119, v5, v4
	v_exp_f32_e32 v132, v10
	v_add_f32_e32 v15, v9, v131
	s_waitcnt lgkmcnt(0)
	v_mfma_f32_32x32x16_bf16 v[82:97], v[238:241], v[158:161], v[82:97]
	v_cvt_pk_bf16_f32 v8, v9, v14
	v_pk_add_f32 v[10:11], v[14:15], v[132:133]
	s_nop 0
	v_add_f32_e32 v119, v10, v11
	v_fma_f32 v10, v136, v5, v4
	v_exp_f32_e32 v15, v10
	v_fma_f32 v10, v120, v5, v4
	v_exp_f32_e32 v133, v10
	v_fma_f32 v10, v137, v5, v4
	v_exp_f32_e32 v16, v10
	v_fma_f32 v10, v121, v5, v4
	v_exp_f32_e32 v118, v10
	v_add_f32_e32 v17, v15, v133
	v_cvt_pk_bf16_f32 v9, v15, v16
	v_pk_add_f32 v[10:11], v[16:17], v[118:119]
	s_nop 0
	v_add_f32_e32 v121, v10, v11
	v_fma_f32 v10, v138, v5, v4
	v_exp_f32_e32 v119, v10
	v_fma_f32 v10, v122, v5, v4
	v_exp_f32_e32 v248, v10
	v_fma_f32 v10, v139, v5, v4
	v_exp_f32_e32 v122, v10
	v_fma_f32 v10, v123, v5, v4
	v_exp_f32_e32 v120, v10
	v_fma_f32 v10, v140, v5, v4
	v_exp_f32_e32 v139, v10
	v_fma_f32 v10, v124, v5, v4
	v_add_f32_e32 v123, v119, v248
	v_exp_f32_e32 v140, v10
	v_pk_add_f32 v[10:11], v[122:123], v[120:121]
	v_fma_f32 v123, v144, v5, v4
	v_add_f32_e32 v135, v10, v11
	v_fma_f32 v10, v141, v5, v4
	v_exp_f32_e32 v136, v10
	v_fma_f32 v10, v125, v5, v4
	v_exp_f32_e32 v134, v10
	ds_read_b64_tr_b16 v[10:11], v218 offset:24576
	ds_read_b64_tr_b16 v[12:13], v218 offset:25600
	ds_read_b64_tr_b16 v[14:15], v217 offset:24640
	ds_read_b64_tr_b16 v[16:17], v217 offset:25664
	ds_read_b64_tr_b16 v[114:115], v218 offset:26624
	ds_read_b64_tr_b16 v[116:117], v218 offset:27648
	s_waitcnt lgkmcnt(4)
	v_mfma_f32_32x32x16_bf16 v[66:81], v[10:13], v[6:9], v[66:81]
	v_fma_f32 v10, v142, v5, v4
	v_exp_f32_e32 v125, v10
	v_fma_f32 v10, v143, v5, v4
	v_exp_f32_e32 v124, v10
	v_exp_f32_e32 v142, v123
	v_add_f32_e32 v137, v139, v140
	ds_read_b64_tr_b16 v[10:11], v217 offset:26688
	ds_read_b64_tr_b16 v[12:13], v217 offset:27712
	s_waitcnt lgkmcnt(4)
	v_mfma_f32_32x32x16_bf16 v[50:65], v[14:17], v[6:9], v[50:65]
	v_fma_f32 v6, v145, v5, v4
	v_exp_f32_e32 v138, v6
	v_cvt_pk_bf16_f32 v6, v119, v122
	v_cvt_pk_bf16_f32 v7, v139, v136
	v_cvt_pk_bf16_f32 v8, v125, v124
	v_cvt_pk_bf16_f32 v9, v142, v138
	v_pk_add_f32 v[14:15], v[136:137], v[134:135]
	s_waitcnt lgkmcnt(2)
	v_mfma_f32_32x32x16_bf16 v[66:81], v[114:117], v[6:9], v[66:81]
	v_add_f32_e64 v123, v14, v15
	v_fma_f32 v14, v126, v5, v4
	v_exp_f32_e32 v126, v14
	ds_read_b64_tr_b16 v[14:15], v218 offset:28672
	ds_read_b64_tr_b16 v[16:17], v218 offset:29696
	v_fma_f32 v114, v127, v5, v4
	v_exp_f32_e32 v122, v114
	v_add_f32_e32 v125, v125, v126
	s_waitcnt lgkmcnt(2)
	v_mfma_f32_32x32x16_bf16 v[50:65], v[10:13], v[6:9], v[50:65]
	v_cvt_pk_bf16_f32 v6, v246, v2
	v_cvt_pk_bf16_f32 v7, v247, v130
	v_cvt_pk_bf16_f32 v8, v131, v132
	v_cvt_pk_bf16_f32 v9, v133, v118
	ds_read_b64_tr_b16 v[10:11], v218 offset:30720
	ds_read_b64_tr_b16 v[12:13], v218 offset:31744
	v_pk_add_f32 v[114:115], v[124:125], v[122:123]
	v_fma_f32 v2, v128, v5, v4
	s_waitcnt lgkmcnt(2)
	v_mfma_f32_32x32x16_bf16 v[66:81], v[14:17], v[6:9], v[66:81]
	ds_read_b64_tr_b16 v[14:15], v217 offset:28736
	ds_read_b64_tr_b16 v[16:17], v217 offset:29760
	v_add_f32_e64 v119, v114, v115
	v_fmac_f32_e32 v4, v129, v5
	ds_read_b64_tr_b16 v[114:115], v217 offset:30784
	ds_read_b64_tr_b16 v[116:117], v217 offset:31808
	v_exp_f32_e32 v2, v2
	v_exp_f32_e32 v118, v4
	v_cvt_pk_bf16_f32 v4, v248, v120
	s_waitcnt lgkmcnt(2)
	v_mfma_f32_32x32x16_bf16 v[50:65], v[14:17], v[6:9], v[50:65]
	v_cvt_pk_bf16_f32 v5, v140, v134
	v_cvt_pk_bf16_f32 v6, v126, v122
	v_cvt_pk_bf16_f32 v7, v2, v118
	v_add_f32_e32 v139, v142, v2
	v_add_f32_e64 v8, v138, v118
	v_add_f32_e64 v9, v139, v119
	v_add_f32_e32 v2, v8, v9
	v_mfma_f32_32x32x16_bf16 v[66:81], v[10:13], v[4:7], v[66:81]
	v_add_f32_e32 v214, v214, v2
	s_waitcnt lgkmcnt(0)
	v_mfma_f32_32x32x16_bf16 v[50:65], v[114:117], v[4:7], v[50:65]
	s_add_i32 s76, s74, 2
	s_cmp_ge_u32 s76, s51
	s_cbranch_scc0 .LBB0_781

; #define LAS __attribute__((address_space(3)))
; #define MFMA32(a, b, c) __builtin_amdgcn_mfma_f32_32x32x16_bf16((a), (b), (c), 0, 0, 0)
; DI float fexp2(float x) { return __builtin_amdgcn_exp2f(x); }
; DI s16x4 vtr(const LAS unsigned char* p) { return __builtin_bit_cast(s16x4, __builtin_amdgcn_ds_read_tr16_b64_v4i16((LAS v4i16_t*)p)); }
; DI void flash_qk(const LAS unsigned char* kb, const bf16x8 (&qf)[4], f32x16& p0, f32x16& p1, int r32, int h) {
;     ...
;     for (int s = 0; s < 4; ++s) {
;         const int off = r32 * 128 + (((2 * s + h) ^ sw) << 4);
;         const bf16x8 a0 = *(const LAS bf16x8*)(kb + off), a1 = *(const LAS bf16x8*)(kb + off + 4096);
;         p0 = MFMA32(a0, qf[s], p0); p1 = MFMA32(a1, qf[s], p1);
;     }
; DI void flash_pv(FState& st, f32x16& p0, f32x16& p1, bool rowon, const LAS unsigned char* vb, int lane) {
;     ...
;     const float cl = rowon ? SM_C : 0.0f;
;     const float bl = rowon ? ((st.m == NINF) ? 0.0f : -st.m * SM_C) : NINF;
;     float sum = 0.f;
; #pragma unroll
;     for (int r = 0; r < 16; ++r) { p0[r] = fexp2(__builtin_fmaf(p0[r], cl, bl)); p1[r] = fexp2(__builtin_fmaf(p1[r], cl, bl)); sum += p0[r] + p1[r]; }
;     st.l += sum;
;     const int h = lane >> 5;
;     const int vx = (((lane & 15) >> 3) & 1) * 64;
;     const LAS unsigned char* vp = vb + (4 * h + ((lane & 15) >> 2)) * 128 + ((lane >> 4) & 1) * 32 + (lane & 3) * 8;
; #pragma unroll
;     for (int sub = 0; sub < 2; ++sub)
; #pragma unroll
;         for (int s2 = 0; s2 < 2; ++s2) {
;             const bf16x8 pf = pack8h(sub ? p1 : p0, s2);
;             const LAS unsigned char* vq = vp + (32 * sub + 16 * s2) * 128;
;             { const s16x4 lo = vtr(vq + vx), hi = vtr(vq + 1024 + vx); const bf16x8 vf = {lo[0], lo[1], lo[2], lo[3], hi[0], hi[1], hi[2], hi[3]}; st.o0 = MFMA32(vf, pf, st.o0); }
;             { const s16x4 lo = vtr(vq + (64 - vx)), hi = vtr(vq + 1024 + (64 - vx)); const bf16x8 vf = {lo[0], lo[1], lo[2], lo[3], hi[0], hi[1], hi[2], hi[3]}; st.o1 = MFMA32(vf, pf, st.o1); }
;         }
.LBB0_799:
	s_or_b64 exec, exec, s[4:5]
	v_fma_f32 v2, v98, v5, v4
	v_exp_f32_e32 v246, v2
	v_fma_f32 v2, v82, v5, v4
	v_exp_f32_e32 v247, v2
	s_waitcnt lgkmcnt(3)
	v_mfma_f32_32x32x16_bf16 v[130:145], v[226:229], v[154:157], v[130:145]
	v_fma_f32 v2, v99, v5, v4
	v_exp_f32_e32 v10, v2
	v_fma_f32 v2, v83, v5, v4
	v_exp_f32_e32 v2, v2
	v_add_f32_e32 v11, v246, v247
	v_pk_add_f32 v[6:7], v[10:11], v[2:3]
	s_nop 0
	v_add_f32_e32 v99, v6, v7
	v_fma_f32 v6, v100, v5, v4
	v_exp_f32_e32 v11, v6
	s_waitcnt lgkmcnt(2)
	v_mfma_f32_32x32x16_bf16 v[114:129], v[230:233], v[154:157], v[114:129]
	v_fma_f32 v6, v84, v5, v4
	v_exp_f32_e32 v248, v6
	v_fma_f32 v6, v101, v5, v4
	v_exp_f32_e32 v12, v6
	v_fma_f32 v6, v85, v5, v4
	v_exp_f32_e32 v98, v6
	v_add_f32_e32 v13, v11, v248
	v_cvt_pk_bf16_f32 v10, v246, v10
	v_cvt_pk_bf16_f32 v11, v11, v12
	v_pk_add_f32 v[6:7], v[12:13], v[98:99]
	s_waitcnt lgkmcnt(1)
	v_mfma_f32_32x32x16_bf16 v[130:145], v[234:237], v[158:161], v[130:145]
	s_nop 0
	v_add_f32_e32 v101, v6, v7
	v_fma_f32 v6, v102, v5, v4
	v_exp_f32_e32 v13, v6
	v_fma_f32 v6, v86, v5, v4
	v_exp_f32_e32 v99, v6
	v_fma_f32 v6, v103, v5, v4
	v_exp_f32_e32 v14, v6
	v_fma_f32 v6, v87, v5, v4
	v_exp_f32_e32 v100, v6
	s_waitcnt lgkmcnt(0)
	v_mfma_f32_32x32x16_bf16 v[114:129], v[238:241], v[158:161], v[114:129]
	v_add_f32_e32 v15, v13, v99
	v_cvt_pk_bf16_f32 v12, v13, v14
	v_pk_add_f32 v[6:7], v[14:15], v[100:101]
	s_nop 0
	v_add_f32_e32 v87, v6, v7
	v_fma_f32 v6, v104, v5, v4
	v_exp_f32_e32 v15, v6
	v_fma_f32 v6, v88, v5, v4
	v_exp_f32_e32 v101, v6
	v_fma_f32 v6, v105, v5, v4
	v_exp_f32_e32 v16, v6
	v_fma_f32 v6, v89, v5, v4
	v_exp_f32_e32 v86, v6
	v_add_f32_e32 v17, v15, v101
	v_cvt_pk_bf16_f32 v13, v15, v16
	v_pk_add_f32 v[6:7], v[16:17], v[86:87]
	s_nop 0
	v_add_f32_e32 v89, v6, v7
	v_fma_f32 v6, v106, v5, v4
	v_exp_f32_e32 v87, v6
	v_fma_f32 v6, v90, v5, v4
	v_exp_f32_e32 v249, v6
	v_fma_f32 v6, v107, v5, v4
	v_exp_f32_e32 v90, v6
	v_fma_f32 v6, v91, v5, v4
	v_exp_f32_e32 v88, v6
	v_fma_f32 v6, v108, v5, v4
	v_exp_f32_e32 v107, v6
	v_fma_f32 v6, v92, v5, v4
	v_add_f32_e32 v91, v87, v249
	v_exp_f32_e32 v108, v6
	v_pk_add_f32 v[6:7], v[90:91], v[88:89]
	v_fma_f32 v91, v112, v5, v4
	v_add_f32_e32 v103, v6, v7
	v_fma_f32 v6, v109, v5, v4
	v_exp_f32_e32 v104, v6
	v_fma_f32 v6, v93, v5, v4
	v_exp_f32_e32 v102, v6
	ds_read_b64_tr_b16 v[6:7], v218 offset:40960
	ds_read_b64_tr_b16 v[8:9], v218 offset:41984
	ds_read_b64_tr_b16 v[14:15], v217 offset:41024
	ds_read_b64_tr_b16 v[16:17], v217 offset:42048
	ds_read_b64_tr_b16 v[82:83], v218 offset:43008
	ds_read_b64_tr_b16 v[84:85], v218 offset:44032
	s_waitcnt lgkmcnt(4)
	v_mfma_f32_32x32x16_bf16 v[66:81], v[6:9], v[10:13], v[66:81]
	v_fma_f32 v6, v110, v5, v4
	v_exp_f32_e32 v89, v6
	v_fma_f32 v6, v111, v5, v4
	v_exp_f32_e32 v92, v6
	v_exp_f32_e32 v109, v91
	v_add_f32_e32 v105, v107, v108
	ds_read_b64_tr_b16 v[6:7], v217 offset:43072
	ds_read_b64_tr_b16 v[8:9], v217 offset:44096
	s_waitcnt lgkmcnt(4)
	v_mfma_f32_32x32x16_bf16 v[50:65], v[14:17], v[10:13], v[50:65]
	v_fma_f32 v10, v113, v5, v4
	v_exp_f32_e32 v106, v10
	v_cvt_pk_bf16_f32 v10, v87, v90
	v_cvt_pk_bf16_f32 v11, v107, v104
	v_cvt_pk_bf16_f32 v12, v89, v92
	v_cvt_pk_bf16_f32 v13, v109, v106
	v_pk_add_f32 v[14:15], v[104:105], v[102:103]
	s_waitcnt lgkmcnt(2)
	v_mfma_f32_32x32x16_bf16 v[66:81], v[82:85], v[10:13], v[66:81]
	v_add_f32_e64 v91, v14, v15
	v_fma_f32 v14, v94, v5, v4
	v_exp_f32_e32 v94, v14
	ds_read_b64_tr_b16 v[14:15], v218 offset:45056
	ds_read_b64_tr_b16 v[16:17], v218 offset:46080
	v_fma_f32 v82, v95, v5, v4
	v_exp_f32_e32 v90, v82
	v_add_f32_e32 v93, v89, v94
	s_waitcnt lgkmcnt(2)
	v_mfma_f32_32x32x16_bf16 v[50:65], v[6:9], v[10:13], v[50:65]
	v_cvt_pk_bf16_f32 v6, v247, v2
	v_cvt_pk_bf16_f32 v7, v248, v98
	v_cvt_pk_bf16_f32 v8, v99, v100
	v_cvt_pk_bf16_f32 v9, v101, v86
	ds_read_b64_tr_b16 v[10:11], v218 offset:47104
	ds_read_b64_tr_b16 v[12:13], v218 offset:48128
	v_pk_add_f32 v[82:83], v[92:93], v[90:91]
	v_fma_f32 v2, v96, v5, v4
	s_waitcnt lgkmcnt(2)
	v_mfma_f32_32x32x16_bf16 v[66:81], v[14:17], v[6:9], v[66:81]
	ds_read_b64_tr_b16 v[14:15], v217 offset:45120
	ds_read_b64_tr_b16 v[16:17], v217 offset:46144
	v_add_f32_e64 v87, v82, v83
	v_fmac_f32_e32 v4, v97, v5
	ds_read_b64_tr_b16 v[82:83], v217 offset:47168
	ds_read_b64_tr_b16 v[84:85], v217 offset:48192
	v_exp_f32_e32 v2, v2
	v_exp_f32_e32 v86, v4
	v_cvt_pk_bf16_f32 v4, v249, v88
	s_waitcnt lgkmcnt(2)
	v_mfma_f32_32x32x16_bf16 v[50:65], v[14:17], v[6:9], v[50:65]
	v_cvt_pk_bf16_f32 v5, v108, v102
	v_cvt_pk_bf16_f32 v6, v94, v90
	v_cvt_pk_bf16_f32 v7, v2, v86
	v_add_f32_e32 v107, v109, v2
	v_add_f32_e64 v8, v106, v86
	v_add_f32_e64 v9, v107, v87
	v_add_f32_e32 v2, v8, v9
	v_mfma_f32_32x32x16_bf16 v[66:81], v[10:13], v[4:7], v[66:81]
	v_add_f32_e32 v214, v214, v2
	s_waitcnt lgkmcnt(0)
	v_mfma_f32_32x32x16_bf16 v[50:65], v[82:85], v[4:7], v[50:65]
	s_add_i32 s52, s52, -3
	s_andn2_b64 vcc, exec, s[6:7]
	s_add_i32 s53, s53, 0xc000
	s_cbranch_vccz .LBB0_712

; #define LAS __attribute__((address_space(3)))
; #define MFMA32(a, b, c) __builtin_amdgcn_mfma_f32_32x32x16_bf16((a), (b), (c), 0, 0, 0)
; DI float fexp2(float x) { return __builtin_amdgcn_exp2f(x); }
; DI s16x4 vtr(const LAS unsigned char* p) { return __builtin_bit_cast(s16x4, __builtin_amdgcn_ds_read_tr16_b64_v4i16((LAS v4i16_t*)p)); }
; DI void flash_pv(FState& st, f32x16& p0, f32x16& p1, bool rowon, const LAS unsigned char* vb, int lane) {
;     ...
;     const float cl = rowon ? SM_C : 0.0f;
;     const float bl = rowon ? ((st.m == NINF) ? 0.0f : -st.m * SM_C) : NINF;
;     float sum = 0.f;
; #pragma unroll
;     for (int r = 0; r < 16; ++r) { p0[r] = fexp2(__builtin_fmaf(p0[r], cl, bl)); p1[r] = fexp2(__builtin_fmaf(p1[r], cl, bl)); sum += p0[r] + p1[r]; }
;     st.l += sum;
;     const int h = lane >> 5;
;     const int vx = (((lane & 15) >> 3) & 1) * 64;
;     const LAS unsigned char* vp = vb + (4 * h + ((lane & 15) >> 2)) * 128 + ((lane >> 4) & 1) * 32 + (lane & 3) * 8;
; #pragma unroll
;     for (int sub = 0; sub < 2; ++sub)
; #pragma unroll
;         for (int s2 = 0; s2 < 2; ++s2) {
;             const bf16x8 pf = pack8h(sub ? p1 : p0, s2);
;             const LAS unsigned char* vq = vp + (32 * sub + 16 * s2) * 128;
;             { const s16x4 lo = vtr(vq + vx), hi = vtr(vq + 1024 + vx); const bf16x8 vf = {lo[0], lo[1], lo[2], lo[3], hi[0], hi[1], hi[2], hi[3]}; st.o0 = MFMA32(vf, pf, st.o0); }
;             { const s16x4 lo = vtr(vq + (64 - vx)), hi = vtr(vq + 1024 + (64 - vx)); const bf16x8 vf = {lo[0], lo[1], lo[2], lo[3], hi[0], hi[1], hi[2], hi[3]}; st.o1 = MFMA32(vf, pf, st.o1); }
;         }
.Lnq_759:
	s_or_b64 exec, exec, s[4:5]
	v_fma_f32 v2, v130, v5, v4
	v_exp_f32_e32 v12, v2
	v_fma_f32 v2, v114, v5, v4
	v_exp_f32_e32 v246, v2
	s_waitcnt lgkmcnt(3)
	v_mfma_f32_32x32x16_bf16 v[98:113], v[226:229], v[154:157], v[98:113]
	v_fma_f32 v2, v131, v5, v4
	v_exp_f32_e32 v6, v2
	v_fma_f32 v2, v115, v5, v4
	v_exp_f32_e32 v2, v2
	v_add_f32_e32 v7, v12, v246
	s_add_i32 s77, s74, 1
	s_cmp_ge_u32 s77, s51
	v_pk_add_f32 v[8:9], v[6:7], v[2:3]
	v_fma_f32 v7, v132, v5, v4
	v_add_f32_e32 v131, v8, v9
	s_waitcnt lgkmcnt(2)
	v_mfma_f32_32x32x16_bf16 v[82:97], v[230:233], v[154:157], v[82:97]
	v_fma_f32 v8, v116, v5, v4
	v_exp_f32_e32 v7, v7
	v_exp_f32_e32 v247, v8
	v_fma_f32 v8, v133, v5, v4
	v_fma_f32 v9, v117, v5, v4
	v_exp_f32_e32 v8, v8
	v_exp_f32_e32 v130, v9
	v_add_f32_e32 v9, v7, v247
	v_cvt_pk_bf16_f32 v6, v12, v6
	v_cvt_pk_bf16_f32 v7, v7, v8
	s_waitcnt lgkmcnt(1)
	v_mfma_f32_32x32x16_bf16 v[98:113], v[234:237], v[158:161], v[98:113]
	v_pk_add_f32 v[10:11], v[8:9], v[130:131]
	v_fma_f32 v9, v134, v5, v4
	v_add_f32_e32 v133, v10, v11
	v_fma_f32 v10, v118, v5, v4
	v_exp_f32_e32 v131, v10
	v_fma_f32 v10, v135, v5, v4
	v_exp_f32_e32 v9, v9
	v_exp_f32_e32 v14, v10
	v_fma_f32 v10, v119, v5, v4
	v_exp_f32_e32 v132, v10
	s_waitcnt lgkmcnt(0)
	v_mfma_f32_32x32x16_bf16 v[82:97], v[238:241], v[158:161], v[82:97]
	v_add_f32_e32 v15, v9, v131
	v_cvt_pk_bf16_f32 v8, v9, v14
	v_pk_add_f32 v[10:11], v[14:15], v[132:133]
	s_nop 0
	v_add_f32_e32 v119, v10, v11
	v_fma_f32 v10, v136, v5, v4
	v_exp_f32_e32 v15, v10
	v_fma_f32 v10, v120, v5, v4
	v_exp_f32_e32 v133, v10
	v_fma_f32 v10, v137, v5, v4
	v_exp_f32_e32 v16, v10
	v_fma_f32 v10, v121, v5, v4
	v_exp_f32_e32 v118, v10
	v_add_f32_e32 v17, v15, v133
	v_cvt_pk_bf16_f32 v9, v15, v16
	v_pk_add_f32 v[10:11], v[16:17], v[118:119]
	s_nop 0
	v_add_f32_e32 v121, v10, v11
	v_fma_f32 v10, v138, v5, v4
	v_exp_f32_e32 v119, v10
	v_fma_f32 v10, v122, v5, v4
	v_exp_f32_e32 v248, v10
	v_fma_f32 v10, v139, v5, v4
	v_exp_f32_e32 v122, v10
	v_fma_f32 v10, v123, v5, v4
	v_exp_f32_e32 v120, v10
	v_fma_f32 v10, v140, v5, v4
	v_exp_f32_e32 v139, v10
	v_fma_f32 v10, v124, v5, v4
	v_add_f32_e32 v123, v119, v248
	v_exp_f32_e32 v140, v10
	v_pk_add_f32 v[10:11], v[122:123], v[120:121]
	v_fma_f32 v123, v144, v5, v4
	v_add_f32_e32 v135, v10, v11
	v_fma_f32 v10, v141, v5, v4
	v_exp_f32_e32 v136, v10
	v_fma_f32 v10, v125, v5, v4
	v_exp_f32_e32 v134, v10
	ds_read_b64_tr_b16 v[10:11], v218 offset:8192
	ds_read_b64_tr_b16 v[12:13], v218 offset:9216
	ds_read_b64_tr_b16 v[14:15], v217 offset:8256
	ds_read_b64_tr_b16 v[16:17], v217 offset:9280
	ds_read_b64_tr_b16 v[114:115], v218 offset:10240
	ds_read_b64_tr_b16 v[116:117], v218 offset:11264
	s_waitcnt lgkmcnt(4)
	v_mfma_f32_32x32x16_bf16 v[66:81], v[10:13], v[6:9], v[66:81]
	v_fma_f32 v10, v142, v5, v4
	v_exp_f32_e32 v121, v10
	v_fma_f32 v10, v143, v5, v4
	v_exp_f32_e32 v124, v10
	v_exp_f32_e32 v141, v123
	v_add_f32_e32 v137, v139, v140
	ds_read_b64_tr_b16 v[10:11], v217 offset:10304
	ds_read_b64_tr_b16 v[12:13], v217 offset:11328
	s_waitcnt lgkmcnt(4)
	v_mfma_f32_32x32x16_bf16 v[50:65], v[14:17], v[6:9], v[50:65]
	v_fma_f32 v6, v145, v5, v4
	v_exp_f32_e32 v138, v6
	v_cvt_pk_bf16_f32 v6, v119, v122
	v_cvt_pk_bf16_f32 v7, v139, v136
	v_cvt_pk_bf16_f32 v8, v121, v124
	v_cvt_pk_bf16_f32 v9, v141, v138
	v_pk_add_f32 v[14:15], v[136:137], v[134:135]
	s_waitcnt lgkmcnt(2)
	v_mfma_f32_32x32x16_bf16 v[66:81], v[114:117], v[6:9], v[66:81]
	v_add_f32_e64 v123, v14, v15
	v_fma_f32 v14, v126, v5, v4
	v_exp_f32_e32 v126, v14
	ds_read_b64_tr_b16 v[14:15], v218 offset:12288
	ds_read_b64_tr_b16 v[16:17], v218 offset:13312
	v_fma_f32 v114, v127, v5, v4
	v_exp_f32_e32 v122, v114
	v_add_f32_e32 v125, v121, v126
	s_waitcnt lgkmcnt(2)
	v_mfma_f32_32x32x16_bf16 v[50:65], v[10:13], v[6:9], v[50:65]
	v_cvt_pk_bf16_f32 v6, v246, v2
	v_cvt_pk_bf16_f32 v7, v247, v130
	v_cvt_pk_bf16_f32 v8, v131, v132
	v_cvt_pk_bf16_f32 v9, v133, v118
	ds_read_b64_tr_b16 v[10:11], v218 offset:14336
	ds_read_b64_tr_b16 v[12:13], v218 offset:15360
	v_pk_add_f32 v[114:115], v[124:125], v[122:123]
	v_fma_f32 v2, v128, v5, v4
	s_waitcnt lgkmcnt(2)
	v_mfma_f32_32x32x16_bf16 v[66:81], v[14:17], v[6:9], v[66:81]
	ds_read_b64_tr_b16 v[14:15], v217 offset:12352
	ds_read_b64_tr_b16 v[16:17], v217 offset:13376
	v_add_f32_e64 v119, v114, v115
	v_fmac_f32_e32 v4, v129, v5
	ds_read_b64_tr_b16 v[114:115], v217 offset:14400
	ds_read_b64_tr_b16 v[116:117], v217 offset:15424
	v_exp_f32_e32 v2, v2
	v_exp_f32_e32 v118, v4
	v_cvt_pk_bf16_f32 v4, v248, v120
	s_waitcnt lgkmcnt(2)
	v_mfma_f32_32x32x16_bf16 v[50:65], v[14:17], v[6:9], v[50:65]
	v_cvt_pk_bf16_f32 v5, v140, v134
	v_cvt_pk_bf16_f32 v6, v126, v122
	v_cvt_pk_bf16_f32 v7, v2, v118
	v_add_f32_e32 v139, v141, v2
	v_add_f32_e64 v8, v138, v118
	v_add_f32_e64 v9, v139, v119
	v_add_f32_e32 v2, v8, v9
	v_mfma_f32_32x32x16_bf16 v[66:81], v[10:13], v[4:7], v[66:81]
	v_add_f32_e32 v214, v214, v2
	s_waitcnt lgkmcnt(0)
	v_mfma_f32_32x32x16_bf16 v[50:65], v[114:117], v[4:7], v[50:65]
	s_cbranch_scc1 .Lnq_780
	s_movk_i32 s76, 0x4000
	s_add_i32 s4, s74, 5
	s_cmp_ge_u32 s4, s51
	s_waitcnt vmcnt(1)
	ds_write_b128 v205, v[182:185] offset:32768
	s_waitcnt vmcnt(0)
	ds_write_b128 v212, v[178:181] offset:40960
	s_waitcnt lgkmcnt(0)
	s_barrier
	s_cbranch_scc1 .Lnq_762
	s_cmp_gt_u32 s4, s69
	s_cselect_b64 s[8:9], -1, 0
	s_mov_b32 s5, s52
	s_and_b64 s[8:9], s[8:9], exec
	s_cselect_b32 s4, s5, s4
	s_cselect_b32 s16, 0x1000, s65
	s_cselect_b32 s8, s64, 0x500
	s_lshl_b32 s4, s4, 6
	s_mov_b32 s9, s17
	v_mad_i64_i32 v[4:5], s[4:5], s4, v199, v[192:193]
	v_lshl_add_u64 v[6:7], v[4:5], 0, s[8:9]
	v_lshl_add_u64 v[4:5], v[4:5], 0, s[16:17]
	global_load_dwordx4 v[182:185], v[6:7], off
	global_load_dwordx4 v[178:181], v[4:5], off

; #define LAS __attribute__((address_space(3)))
; #define MFMA32(a, b, c) __builtin_amdgcn_mfma_f32_32x32x16_bf16((a), (b), (c), 0, 0, 0)
; DI float fexp2(float x) { return __builtin_amdgcn_exp2f(x); }
; DI s16x4 vtr(const LAS unsigned char* p) { return __builtin_bit_cast(s16x4, __builtin_amdgcn_ds_read_tr16_b64_v4i16((LAS v4i16_t*)p)); }
; DI void flash_qk(const LAS unsigned char* kb, const bf16x8 (&qf)[4], f32x16& p0, f32x16& p1, int r32, int h) {
;     ...
;     for (int s = 0; s < 4; ++s) {
;         const int off = r32 * 128 + (((2 * s + h) ^ sw) << 4);
;         const bf16x8 a0 = *(const LAS bf16x8*)(kb + off), a1 = *(const LAS bf16x8*)(kb + off + 4096);
;         p0 = MFMA32(a0, qf[s], p0); p1 = MFMA32(a1, qf[s], p1);
;     }
; DI void flash_pv(FState& st, f32x16& p0, f32x16& p1, bool rowon, const LAS unsigned char* vb, int lane) {
;     ...
;     const float cl = rowon ? SM_C : 0.0f;
;     const float bl = rowon ? ((st.m == NINF) ? 0.0f : -st.m * SM_C) : NINF;
;     float sum = 0.f;
; #pragma unroll
;     for (int r = 0; r < 16; ++r) { p0[r] = fexp2(__builtin_fmaf(p0[r], cl, bl)); p1[r] = fexp2(__builtin_fmaf(p1[r], cl, bl)); sum += p0[r] + p1[r]; }
;     st.l += sum;
;     const int h = lane >> 5;
;     const int vx = (((lane & 15) >> 3) & 1) * 64;
;     const LAS unsigned char* vp = vb + (4 * h + ((lane & 15) >> 2)) * 128 + ((lane >> 4) & 1) * 32 + (lane & 3) * 8;
; #pragma unroll
;     for (int sub = 0; sub < 2; ++sub)
; #pragma unroll
;         for (int s2 = 0; s2 < 2; ++s2) {
;             const bf16x8 pf = pack8h(sub ? p1 : p0, s2);
;             const LAS unsigned char* vq = vp + (32 * sub + 16 * s2) * 128;
;             { const s16x4 lo = vtr(vq + vx), hi = vtr(vq + 1024 + vx); const bf16x8 vf = {lo[0], lo[1], lo[2], lo[3], hi[0], hi[1], hi[2], hi[3]}; st.o0 = MFMA32(vf, pf, st.o0); }
;             { const s16x4 lo = vtr(vq + (64 - vx)), hi = vtr(vq + 1024 + (64 - vx)); const bf16x8 vf = {lo[0], lo[1], lo[2], lo[3], hi[0], hi[1], hi[2], hi[3]}; st.o1 = MFMA32(vf, pf, st.o1); }
;         }
.Lnq_778:
	s_or_b64 exec, exec, s[4:5]
	v_fma_f32 v2, v98, v5, v4
	v_exp_f32_e32 v12, v2
	v_fma_f32 v2, v82, v5, v4
	v_exp_f32_e32 v246, v2
	s_waitcnt lgkmcnt(3)
	v_mfma_f32_32x32x16_bf16 v[130:145], v[226:229], v[154:157], v[130:145]
	v_fma_f32 v2, v99, v5, v4
	v_exp_f32_e32 v6, v2
	v_fma_f32 v2, v83, v5, v4
	v_exp_f32_e32 v2, v2
	v_add_f32_e32 v7, v12, v246
	v_pk_add_f32 v[8:9], v[6:7], v[2:3]
	s_nop 0
	v_add_f32_e32 v99, v8, v9
	v_fma_f32 v7, v100, v5, v4
	v_fma_f32 v8, v84, v5, v4
	s_waitcnt lgkmcnt(2)
	v_mfma_f32_32x32x16_bf16 v[114:129], v[230:233], v[154:157], v[114:129]
	v_exp_f32_e32 v7, v7
	v_exp_f32_e32 v247, v8
	v_fma_f32 v8, v101, v5, v4
	v_fma_f32 v9, v85, v5, v4
	v_exp_f32_e32 v8, v8
	v_exp_f32_e32 v98, v9
	v_add_f32_e32 v9, v7, v247
	v_cvt_pk_bf16_f32 v6, v12, v6
	v_cvt_pk_bf16_f32 v7, v7, v8
	v_pk_add_f32 v[10:11], v[8:9], v[98:99]
	s_waitcnt lgkmcnt(1)
	v_mfma_f32_32x32x16_bf16 v[130:145], v[234:237], v[158:161], v[130:145]
	v_fma_f32 v9, v102, v5, v4
	v_add_f32_e32 v101, v10, v11
	v_fma_f32 v10, v86, v5, v4
	v_exp_f32_e32 v99, v10
	v_fma_f32 v10, v103, v5, v4
	v_exp_f32_e32 v9, v9
	v_exp_f32_e32 v14, v10
	v_fma_f32 v10, v87, v5, v4
	v_exp_f32_e32 v100, v10
	v_add_f32_e32 v15, v9, v99
	s_waitcnt lgkmcnt(0)
	v_mfma_f32_32x32x16_bf16 v[114:129], v[238:241], v[158:161], v[114:129]
	v_cvt_pk_bf16_f32 v8, v9, v14
	v_pk_add_f32 v[10:11], v[14:15], v[100:101]
	s_nop 0
	v_add_f32_e32 v87, v10, v11
	v_fma_f32 v10, v104, v5, v4
	v_exp_f32_e32 v15, v10
	v_fma_f32 v10, v88, v5, v4
	v_exp_f32_e32 v101, v10
	v_fma_f32 v10, v105, v5, v4
	v_exp_f32_e32 v16, v10
	v_fma_f32 v10, v89, v5, v4
	v_exp_f32_e32 v86, v10
	v_add_f32_e32 v17, v15, v101
	v_cvt_pk_bf16_f32 v9, v15, v16
	v_pk_add_f32 v[10:11], v[16:17], v[86:87]
	s_nop 0
	v_add_f32_e32 v89, v10, v11
	v_fma_f32 v10, v106, v5, v4
	v_exp_f32_e32 v87, v10
	v_fma_f32 v10, v90, v5, v4
	v_exp_f32_e32 v248, v10
	v_fma_f32 v10, v107, v5, v4
	v_exp_f32_e32 v90, v10
	v_fma_f32 v10, v91, v5, v4
	v_exp_f32_e32 v88, v10
	v_fma_f32 v10, v108, v5, v4
	v_exp_f32_e32 v107, v10
	v_fma_f32 v10, v92, v5, v4
	v_add_f32_e32 v91, v87, v248
	v_exp_f32_e32 v108, v10
	v_pk_add_f32 v[10:11], v[90:91], v[88:89]
	v_fma_f32 v91, v112, v5, v4
	v_add_f32_e32 v103, v10, v11
	v_fma_f32 v10, v109, v5, v4
	v_exp_f32_e32 v104, v10
	v_fma_f32 v10, v93, v5, v4
	v_exp_f32_e32 v102, v10
	ds_read_b64_tr_b16 v[10:11], v218 offset:24576
	ds_read_b64_tr_b16 v[12:13], v218 offset:25600
	ds_read_b64_tr_b16 v[14:15], v217 offset:24640
	ds_read_b64_tr_b16 v[16:17], v217 offset:25664
	ds_read_b64_tr_b16 v[82:83], v218 offset:26624
	ds_read_b64_tr_b16 v[84:85], v218 offset:27648
	s_waitcnt lgkmcnt(4)
	v_mfma_f32_32x32x16_bf16 v[66:81], v[10:13], v[6:9], v[66:81]
	v_fma_f32 v10, v110, v5, v4
	v_exp_f32_e32 v93, v10
	v_fma_f32 v10, v111, v5, v4
	v_exp_f32_e32 v92, v10
	v_exp_f32_e32 v110, v91
	v_add_f32_e32 v105, v107, v108
	ds_read_b64_tr_b16 v[10:11], v217 offset:26688
	ds_read_b64_tr_b16 v[12:13], v217 offset:27712
	s_waitcnt lgkmcnt(4)
	v_mfma_f32_32x32x16_bf16 v[50:65], v[14:17], v[6:9], v[50:65]
	v_fma_f32 v6, v113, v5, v4
	v_exp_f32_e32 v106, v6
	v_cvt_pk_bf16_f32 v6, v87, v90
	v_cvt_pk_bf16_f32 v7, v107, v104
	v_cvt_pk_bf16_f32 v8, v93, v92
	v_cvt_pk_bf16_f32 v9, v110, v106
	v_pk_add_f32 v[14:15], v[104:105], v[102:103]
	s_waitcnt lgkmcnt(2)
	v_mfma_f32_32x32x16_bf16 v[66:81], v[82:85], v[6:9], v[66:81]
	v_add_f32_e64 v91, v14, v15
	v_fma_f32 v14, v94, v5, v4
	v_exp_f32_e32 v94, v14
	ds_read_b64_tr_b16 v[14:15], v218 offset:28672
	ds_read_b64_tr_b16 v[16:17], v218 offset:29696
	v_fma_f32 v82, v95, v5, v4
	v_exp_f32_e32 v90, v82
	v_add_f32_e32 v93, v93, v94
	s_waitcnt lgkmcnt(2)
	v_mfma_f32_32x32x16_bf16 v[50:65], v[10:13], v[6:9], v[50:65]
	v_cvt_pk_bf16_f32 v6, v246, v2
	v_cvt_pk_bf16_f32 v7, v247, v98
	v_cvt_pk_bf16_f32 v8, v99, v100
	v_cvt_pk_bf16_f32 v9, v101, v86
	ds_read_b64_tr_b16 v[10:11], v218 offset:30720
	ds_read_b64_tr_b16 v[12:13], v218 offset:31744
	v_pk_add_f32 v[82:83], v[92:93], v[90:91]
	v_fma_f32 v2, v96, v5, v4
	s_waitcnt lgkmcnt(2)
	v_mfma_f32_32x32x16_bf16 v[66:81], v[14:17], v[6:9], v[66:81]
	ds_read_b64_tr_b16 v[14:15], v217 offset:28736
	ds_read_b64_tr_b16 v[16:17], v217 offset:29760
	v_add_f32_e64 v87, v82, v83
	v_fmac_f32_e32 v4, v97, v5
	ds_read_b64_tr_b16 v[82:83], v217 offset:30784
	ds_read_b64_tr_b16 v[84:85], v217 offset:31808
	v_exp_f32_e32 v2, v2
	v_exp_f32_e32 v86, v4
	v_cvt_pk_bf16_f32 v4, v248, v88
	s_waitcnt lgkmcnt(2)
	v_mfma_f32_32x32x16_bf16 v[50:65], v[14:17], v[6:9], v[50:65]
	v_cvt_pk_bf16_f32 v5, v108, v102
	v_cvt_pk_bf16_f32 v6, v94, v90
	v_cvt_pk_bf16_f32 v7, v2, v86
	v_add_f32_e32 v107, v110, v2
	v_add_f32_e64 v8, v106, v86
	v_add_f32_e64 v9, v107, v87
	v_add_f32_e32 v2, v8, v9
	v_mfma_f32_32x32x16_bf16 v[66:81], v[10:13], v[4:7], v[66:81]
	v_add_f32_e32 v214, v214, v2
	s_waitcnt lgkmcnt(0)
	v_mfma_f32_32x32x16_bf16 v[50:65], v[82:85], v[4:7], v[50:65]
	s_add_i32 s76, s74, 2
	s_cmp_ge_u32 s76, s51
	s_cbranch_scc0 .Lnq_781

; #define LAS __attribute__((address_space(3)))
; #define MFMA32(a, b, c) __builtin_amdgcn_mfma_f32_32x32x16_bf16((a), (b), (c), 0, 0, 0)
; DI float fexp2(float x) { return __builtin_amdgcn_exp2f(x); }
; DI s16x4 vtr(const LAS unsigned char* p) { return __builtin_bit_cast(s16x4, __builtin_amdgcn_ds_read_tr16_b64_v4i16((LAS v4i16_t*)p)); }
; DI void flash_qk(const LAS unsigned char* kb, const bf16x8 (&qf)[4], f32x16& p0, f32x16& p1, int r32, int h) {
;     ...
;     for (int s = 0; s < 4; ++s) {
;         const int off = r32 * 128 + (((2 * s + h) ^ sw) << 4);
;         const bf16x8 a0 = *(const LAS bf16x8*)(kb + off), a1 = *(const LAS bf16x8*)(kb + off + 4096);
;         p0 = MFMA32(a0, qf[s], p0); p1 = MFMA32(a1, qf[s], p1);
;     }
; DI void flash_pv(FState& st, f32x16& p0, f32x16& p1, bool rowon, const LAS unsigned char* vb, int lane) {
;     ...
;     const float cl = rowon ? SM_C : 0.0f;
;     const float bl = rowon ? ((st.m == NINF) ? 0.0f : -st.m * SM_C) : NINF;
;     float sum = 0.f;
; #pragma unroll
;     for (int r = 0; r < 16; ++r) { p0[r] = fexp2(__builtin_fmaf(p0[r], cl, bl)); p1[r] = fexp2(__builtin_fmaf(p1[r], cl, bl)); sum += p0[r] + p1[r]; }
;     st.l += sum;
;     const int h = lane >> 5;
;     const int vx = (((lane & 15) >> 3) & 1) * 64;
;     const LAS unsigned char* vp = vb + (4 * h + ((lane & 15) >> 2)) * 128 + ((lane >> 4) & 1) * 32 + (lane & 3) * 8;
; #pragma unroll
;     for (int sub = 0; sub < 2; ++sub)
; #pragma unroll
;         for (int s2 = 0; s2 < 2; ++s2) {
;             const bf16x8 pf = pack8h(sub ? p1 : p0, s2);
;             const LAS unsigned char* vq = vp + (32 * sub + 16 * s2) * 128;
;             { const s16x4 lo = vtr(vq + vx), hi = vtr(vq + 1024 + vx); const bf16x8 vf = {lo[0], lo[1], lo[2], lo[3], hi[0], hi[1], hi[2], hi[3]}; st.o0 = MFMA32(vf, pf, st.o0); }
;             { const s16x4 lo = vtr(vq + (64 - vx)), hi = vtr(vq + 1024 + (64 - vx)); const bf16x8 vf = {lo[0], lo[1], lo[2], lo[3], hi[0], hi[1], hi[2], hi[3]}; st.o1 = MFMA32(vf, pf, st.o1); }
;         }
.Lnq_799:
	s_or_b64 exec, exec, s[4:5]
	v_fma_f32 v2, v130, v5, v4
	v_exp_f32_e32 v246, v2
	v_fma_f32 v2, v114, v5, v4
	v_exp_f32_e32 v247, v2
	s_waitcnt lgkmcnt(3)
	v_mfma_f32_32x32x16_bf16 v[98:113], v[226:229], v[154:157], v[98:113]
	v_fma_f32 v2, v131, v5, v4
	v_exp_f32_e32 v10, v2
	v_fma_f32 v2, v115, v5, v4
	v_exp_f32_e32 v2, v2
	v_add_f32_e32 v11, v246, v247
	v_pk_add_f32 v[6:7], v[10:11], v[2:3]
	s_nop 0
	v_add_f32_e32 v131, v6, v7
	v_fma_f32 v6, v132, v5, v4
	v_exp_f32_e32 v11, v6
	s_waitcnt lgkmcnt(2)
	v_mfma_f32_32x32x16_bf16 v[82:97], v[230:233], v[154:157], v[82:97]
	v_fma_f32 v6, v116, v5, v4
	v_exp_f32_e32 v248, v6
	v_fma_f32 v6, v133, v5, v4
	v_exp_f32_e32 v12, v6
	v_fma_f32 v6, v117, v5, v4
	v_exp_f32_e32 v130, v6
	v_add_f32_e32 v13, v11, v248
	v_cvt_pk_bf16_f32 v10, v246, v10
	v_cvt_pk_bf16_f32 v11, v11, v12
	v_pk_add_f32 v[6:7], v[12:13], v[130:131]
	s_waitcnt lgkmcnt(1)
	v_mfma_f32_32x32x16_bf16 v[98:113], v[234:237], v[158:161], v[98:113]
	s_nop 0
	v_add_f32_e32 v133, v6, v7
	v_fma_f32 v6, v134, v5, v4
	v_exp_f32_e32 v13, v6
	v_fma_f32 v6, v118, v5, v4
	v_exp_f32_e32 v131, v6
	v_fma_f32 v6, v135, v5, v4
	v_exp_f32_e32 v14, v6
	v_fma_f32 v6, v119, v5, v4
	v_exp_f32_e32 v132, v6
	s_waitcnt lgkmcnt(0)
	v_mfma_f32_32x32x16_bf16 v[82:97], v[238:241], v[158:161], v[82:97]
	v_add_f32_e32 v15, v13, v131
	v_cvt_pk_bf16_f32 v12, v13, v14
	v_pk_add_f32 v[6:7], v[14:15], v[132:133]
	s_nop 0
	v_add_f32_e32 v119, v6, v7
	v_fma_f32 v6, v136, v5, v4
	v_exp_f32_e32 v15, v6
	v_fma_f32 v6, v120, v5, v4
	v_exp_f32_e32 v133, v6
	v_fma_f32 v6, v137, v5, v4
	v_exp_f32_e32 v16, v6
	v_fma_f32 v6, v121, v5, v4
	v_exp_f32_e32 v118, v6
	v_add_f32_e32 v17, v15, v133
	v_cvt_pk_bf16_f32 v13, v15, v16
	v_pk_add_f32 v[6:7], v[16:17], v[118:119]
	s_nop 0
	v_add_f32_e32 v121, v6, v7
	v_fma_f32 v6, v138, v5, v4
	v_exp_f32_e32 v119, v6
	v_fma_f32 v6, v122, v5, v4
	v_exp_f32_e32 v249, v6
	v_fma_f32 v6, v139, v5, v4
	v_exp_f32_e32 v122, v6
	v_fma_f32 v6, v123, v5, v4
	v_exp_f32_e32 v120, v6
	v_fma_f32 v6, v140, v5, v4
	v_exp_f32_e32 v139, v6
	v_fma_f32 v6, v124, v5, v4
	v_add_f32_e32 v123, v119, v249
	v_exp_f32_e32 v140, v6
	v_pk_add_f32 v[6:7], v[122:123], v[120:121]
	v_fma_f32 v123, v144, v5, v4
	v_add_f32_e32 v135, v6, v7
	v_fma_f32 v6, v141, v5, v4
	v_exp_f32_e32 v136, v6
	v_fma_f32 v6, v125, v5, v4
	v_exp_f32_e32 v134, v6
	ds_read_b64_tr_b16 v[6:7], v218 offset:40960
	ds_read_b64_tr_b16 v[8:9], v218 offset:41984
	ds_read_b64_tr_b16 v[14:15], v217 offset:41024
	ds_read_b64_tr_b16 v[16:17], v217 offset:42048
	ds_read_b64_tr_b16 v[114:115], v218 offset:43008
	ds_read_b64_tr_b16 v[116:117], v218 offset:44032
	s_waitcnt lgkmcnt(4)
	v_mfma_f32_32x32x16_bf16 v[66:81], v[6:9], v[10:13], v[66:81]
	v_fma_f32 v6, v142, v5, v4
	v_exp_f32_e32 v121, v6
	v_fma_f32 v6, v143, v5, v4
	v_exp_f32_e32 v124, v6
	v_exp_f32_e32 v141, v123
	v_add_f32_e32 v137, v139, v140
	ds_read_b64_tr_b16 v[6:7], v217 offset:43072
	ds_read_b64_tr_b16 v[8:9], v217 offset:44096
	s_waitcnt lgkmcnt(4)
	v_mfma_f32_32x32x16_bf16 v[50:65], v[14:17], v[10:13], v[50:65]
	v_fma_f32 v10, v145, v5, v4
	v_exp_f32_e32 v138, v10
	v_cvt_pk_bf16_f32 v10, v119, v122
	v_cvt_pk_bf16_f32 v11, v139, v136
	v_cvt_pk_bf16_f32 v12, v121, v124
	v_cvt_pk_bf16_f32 v13, v141, v138
	v_pk_add_f32 v[14:15], v[136:137], v[134:135]
	s_waitcnt lgkmcnt(2)
	v_mfma_f32_32x32x16_bf16 v[66:81], v[114:117], v[10:13], v[66:81]
	v_add_f32_e64 v123, v14, v15
	v_fma_f32 v14, v126, v5, v4
	v_exp_f32_e32 v126, v14
	ds_read_b64_tr_b16 v[14:15], v218 offset:45056
	ds_read_b64_tr_b16 v[16:17], v218 offset:46080
	v_fma_f32 v114, v127, v5, v4
	v_exp_f32_e32 v122, v114
	v_add_f32_e32 v125, v121, v126
	s_waitcnt lgkmcnt(2)
	v_mfma_f32_32x32x16_bf16 v[50:65], v[6:9], v[10:13], v[50:65]
	v_cvt_pk_bf16_f32 v6, v247, v2
	v_cvt_pk_bf16_f32 v7, v248, v130
	v_cvt_pk_bf16_f32 v8, v131, v132
	v_cvt_pk_bf16_f32 v9, v133, v118
	ds_read_b64_tr_b16 v[10:11], v218 offset:47104
	ds_read_b64_tr_b16 v[12:13], v218 offset:48128
	v_pk_add_f32 v[114:115], v[124:125], v[122:123]
	v_fma_f32 v2, v128, v5, v4
	s_waitcnt lgkmcnt(2)
	v_mfma_f32_32x32x16_bf16 v[66:81], v[14:17], v[6:9], v[66:81]
	ds_read_b64_tr_b16 v[14:15], v217 offset:45120
	ds_read_b64_tr_b16 v[16:17], v217 offset:46144
	v_add_f32_e64 v119, v114, v115
	v_fmac_f32_e32 v4, v129, v5
	ds_read_b64_tr_b16 v[114:115], v217 offset:47168
	ds_read_b64_tr_b16 v[116:117], v217 offset:48192
	v_exp_f32_e32 v2, v2
	v_exp_f32_e32 v118, v4
	v_cvt_pk_bf16_f32 v4, v249, v120
	s_waitcnt lgkmcnt(2)
	v_mfma_f32_32x32x16_bf16 v[50:65], v[14:17], v[6:9], v[50:65]
	v_cvt_pk_bf16_f32 v5, v140, v134
	v_cvt_pk_bf16_f32 v6, v126, v122
	v_cvt_pk_bf16_f32 v7, v2, v118
	v_add_f32_e32 v139, v141, v2
	v_add_f32_e64 v8, v138, v118
	v_add_f32_e64 v9, v139, v119
	v_add_f32_e32 v2, v8, v9
	v_mfma_f32_32x32x16_bf16 v[66:81], v[10:13], v[4:7], v[66:81]
	v_add_f32_e32 v214, v214, v2
	s_waitcnt lgkmcnt(0)
	v_mfma_f32_32x32x16_bf16 v[50:65], v[114:117], v[4:7], v[50:65]
	s_add_i32 s52, s52, -3
	s_andn2_b64 vcc, exec, s[6:7]
	s_add_i32 s53, s53, 0xc000
	s_cbranch_vccz .LBB0_712
